# v68 + shared reciprocal for silu pairs in scan conv stage (28 pairs: 2 rcp -> mul+rcp+pk_mul)
# speedup vs baseline: 1.0158x; 1.0002x over previous
.LBB0_781:
	s_lshl_b32 s0, s35, 11
	v_mov_b32_e32 v16, v144
	s_and_b32 s0, s0, 0x800
	s_add_i32 s36, s0, 0
	v_and_b32_e32 v137, 15, v16
	v_lshrrev_b32_e32 v16, 1, v16
	s_add_i32 s36, s36, 0x22000
	v_and_b32_e32 v138, 0x78, v16
	v_lshl_add_u32 v51, v137, 5, s30
	v_lshl_add_u32 v20, v138, 2, s36
	v_add_u32_e32 v136, 0x800, v51
	ds_read_b128 v[16:19], v20 offset:1040
	ds_read2_b64 v[42:45], v51 offset1:160
	ds_read2_b64 v[116:119], v136 offset0:64 offset1:224
	ds_read_b128 v[20:23], v20 offset:1024
	ds_read_b64 v[46:47], v51 offset:5120
	s_waitcnt vmcnt(8)
	v_lshlrev_b32_e32 v24, 16, v52
	v_and_b32_e32 v25, 0xffff0000, v52
	v_lshlrev_b32_e32 v26, 16, v56
	v_and_b32_e32 v27, 0xffff0000, v56
	s_waitcnt lgkmcnt(0)
	v_pk_fma_f32 v[24:25], v[42:43], v[24:25], v[46:47]
	v_lshlrev_b32_e32 v28, 16, v60
	v_and_b32_e32 v29, 0xffff0000, v60
	v_pk_fma_f32 v[24:25], v[44:45], v[26:27], v[24:25]
	v_pk_fma_f32 v[26:27], v[42:43], v[26:27], v[46:47]
	s_waitcnt vmcnt(7)
	v_lshlrev_b32_e32 v30, 16, v64
	v_and_b32_e32 v31, 0xffff0000, v64
	v_pk_fma_f32 v[26:27], v[44:45], v[28:29], v[26:27]
	s_waitcnt vmcnt(6)
	v_lshlrev_b32_e32 v38, 16, v68
	v_and_b32_e32 v39, 0xffff0000, v68
	v_pk_fma_f32 v[26:27], v[116:117], v[30:31], v[26:27]
	v_pk_fma_f32 v[24:25], v[116:117], v[28:29], v[24:25]
	v_pk_fma_f32 v[26:27], v[118:119], v[38:39], v[26:27]
	v_pk_fma_f32 v[28:29], v[42:43], v[28:29], v[46:47]
	v_pk_mul_f32 v[34:35], v[26:27], s[78:79] op_sel_hi:[1,0]
	v_pk_fma_f32 v[28:29], v[44:45], v[30:31], v[28:29]
	v_exp_f32_e32 v34, v34
	v_exp_f32_e32 v35, v35
	s_waitcnt vmcnt(5)
	v_lshlrev_b32_e32 v40, 16, v72
	v_and_b32_e32 v41, 0xffff0000, v72
	v_pk_fma_f32 v[28:29], v[116:117], v[38:39], v[28:29]
	v_pk_add_f32 v[34:35], v[34:35], 1.0 op_sel_hi:[1,0]
	v_pk_fma_f32 v[28:29], v[118:119], v[40:41], v[28:29]
	v_mul_f32_e32 v242, v34, v35
	v_rcp_f32_e32 v242, v242
	s_nop 0
	v_pk_mul_f32 v[34:35], v[34:35], v[242:243] op_sel:[1,0] op_sel_hi:[0,0]
	v_pk_fma_f32 v[24:25], v[118:119], v[30:31], v[24:25]
	v_pk_fma_f32 v[30:31], v[42:43], v[30:31], v[46:47]
	s_waitcnt vmcnt(4)
	v_lshlrev_b32_e32 v120, 16, v76
	v_pk_mul_f32 v[26:27], v[26:27], v[34:35]
	v_pk_mul_f32 v[34:35], v[28:29], s[78:79] op_sel_hi:[1,0]
	v_pk_fma_f32 v[30:31], v[44:45], v[38:39], v[30:31]
	v_exp_f32_e32 v34, v34
	v_exp_f32_e32 v35, v35
	v_pk_fma_f32 v[38:39], v[42:43], v[38:39], v[46:47]
	v_and_b32_e32 v121, 0xffff0000, v76
	v_pk_fma_f32 v[30:31], v[116:117], v[40:41], v[30:31]
	v_pk_add_f32 v[34:35], v[34:35], 1.0 op_sel_hi:[1,0]
	v_pk_fma_f32 v[38:39], v[44:45], v[40:41], v[38:39]
	v_rcp_f32_e32 v112, v34
	v_rcp_f32_e32 v113, v35
	s_waitcnt vmcnt(3)
	v_lshlrev_b32_e32 v122, 16, v80
	v_and_b32_e32 v123, 0xffff0000, v80
	v_pk_fma_f32 v[30:31], v[118:119], v[120:121], v[30:31]
	v_pk_fma_f32 v[38:39], v[116:117], v[120:121], v[38:39]
	v_pk_mul_f32 v[36:37], v[30:31], s[78:79] op_sel_hi:[1,0]
	v_pk_mul_f32 v[28:29], v[28:29], v[112:113]
	v_pk_fma_f32 v[112:113], v[118:119], v[122:123], v[38:39]
	v_exp_f32_e32 v36, v36
	v_exp_f32_e32 v37, v37
	v_pk_mul_f32 v[38:39], v[112:113], s[78:79] op_sel_hi:[1,0]
	v_pk_fma_f32 v[40:41], v[42:43], v[40:41], v[46:47]
	v_exp_f32_e32 v38, v38
	v_exp_f32_e32 v39, v39
	v_pk_add_f32 v[34:35], v[36:37], 1.0 op_sel_hi:[1,0]
	s_waitcnt vmcnt(2)
	v_lshlrev_b32_e32 v124, 16, v84
	v_rcp_f32_e32 v114, v34
	v_rcp_f32_e32 v115, v35
	v_pk_add_f32 v[38:39], v[38:39], 1.0 op_sel_hi:[1,0]
	v_and_b32_e32 v125, 0xffff0000, v84
	v_pk_fma_f32 v[40:41], v[44:45], v[120:121], v[40:41]
	v_rcp_f32_e32 v130, v38
	v_rcp_f32_e32 v131, v39
	v_pk_fma_f32 v[120:121], v[42:43], v[120:121], v[46:47]
	v_pk_fma_f32 v[42:43], v[42:43], v[122:123], v[46:47]
	s_waitcnt vmcnt(1)
	v_lshlrev_b32_e32 v126, 16, v88
	v_and_b32_e32 v127, 0xffff0000, v88
	v_pk_fma_f32 v[120:121], v[44:45], v[122:123], v[120:121]
	v_pk_fma_f32 v[42:43], v[44:45], v[124:125], v[42:43]
	s_waitcnt vmcnt(0)
	v_lshlrev_b32_e32 v128, 16, v92
	v_and_b32_e32 v129, 0xffff0000, v92
	v_pk_fma_f32 v[40:41], v[116:117], v[122:123], v[40:41]
	v_pk_fma_f32 v[120:121], v[116:117], v[124:125], v[120:121]
	v_pk_fma_f32 v[42:43], v[116:117], v[126:127], v[42:43]
	v_pk_mul_f32 v[32:33], v[24:25], s[78:79] op_sel_hi:[1,0]
	v_pk_mul_f32 v[30:31], v[30:31], v[114:115]
	v_pk_fma_f32 v[114:115], v[118:119], v[124:125], v[40:41]
	v_pk_fma_f32 v[120:121], v[118:119], v[126:127], v[120:121]
	v_pk_fma_f32 v[46:47], v[118:119], v[128:129], v[42:43]
	v_exp_f32_e32 v32, v32
	v_exp_f32_e32 v33, v33
	v_pk_mul_f32 v[40:41], v[114:115], s[78:79] op_sel_hi:[1,0]
	v_pk_mul_f32 v[112:113], v[112:113], v[130:131]
	v_pk_mul_f32 v[130:131], v[120:121], s[78:79] op_sel_hi:[1,0]
	v_pk_mul_f32 v[42:43], v[46:47], s[78:79] op_sel_hi:[1,0]
	v_exp_f32_e32 v40, v40
	v_exp_f32_e32 v41, v41
	v_exp_f32_e32 v130, v130
	v_exp_f32_e32 v131, v131
	v_exp_f32_e32 v42, v42
	v_exp_f32_e32 v43, v43
	v_pk_add_f32 v[32:33], v[32:33], 1.0 op_sel_hi:[1,0]
	v_pk_add_f32 v[38:39], v[40:41], 1.0 op_sel_hi:[1,0]
	v_mul_f32_e32 v244, v32, v33
	v_rcp_f32_e32 v244, v244
	s_nop 0
	v_pk_mul_f32 v[32:33], v[32:33], v[244:245] op_sel:[1,0] op_sel_hi:[0,0]
	v_pk_add_f32 v[44:45], v[130:131], 1.0 op_sel_hi:[1,0]
	v_pk_add_f32 v[42:43], v[42:43], 1.0 op_sel_hi:[1,0]
	v_rcp_f32_e32 v132, v38
	v_rcp_f32_e32 v133, v39
	v_mul_f32_e32 v246, v44, v45
	v_rcp_f32_e32 v246, v246
	s_nop 0
	v_pk_mul_f32 v[44:45], v[44:45], v[246:247] op_sel:[1,0] op_sel_hi:[0,0]
	v_rcp_f32_e32 v118, v42
	v_rcp_f32_e32 v119, v43
	v_pk_mul_f32 v[24:25], v[24:25], v[32:33]
	v_cndmask_b32_e64 v33, 0, 1, s[40:41]
	v_pk_mul_f32 v[114:115], v[114:115], v[132:133]
	v_pk_mul_f32 v[116:117], v[120:121], v[44:45]
	v_pk_mul_f32 v[118:119], v[46:47], v[118:119]
	v_cmp_ne_u32_e64 s[0:1], 1, v33
	s_andn2_b64 vcc, exec, s[40:41]
	v_cvt_pk_bf16_f32 v32, v24, v25
	v_cvt_pk_bf16_f32 v34, v26, v27
	v_cvt_pk_bf16_f32 v36, v28, v29
	v_cvt_pk_bf16_f32 v38, v30, v31
	v_cvt_pk_bf16_f32 v40, v112, v113
	v_cvt_pk_bf16_f32 v42, v114, v115
	v_cvt_pk_bf16_f32 v44, v116, v117
	v_cvt_pk_bf16_f32 v46, v118, v119
	s_cbranch_vccnz .LBB0_783
	v_mul_f32_e32 v24, v20, v24
	v_mul_f32_e32 v26, v21, v26
	v_cvt_pk_bf16_f32 v96, v24, v26
	v_mul_f32_e32 v24, v20, v25
	v_mul_f32_e32 v25, v21, v27
	v_cvt_pk_bf16_f32 v104, v24, v25
	v_mul_f32_e32 v24, v22, v28
	v_mul_f32_e32 v25, v23, v30
	v_cvt_pk_bf16_f32 v97, v24, v25
	v_mul_f32_e32 v24, v22, v29
	v_mul_f32_e32 v25, v23, v31
	v_cvt_pk_bf16_f32 v105, v24, v25
	v_mul_f32_e32 v24, v16, v112
	v_mul_f32_e32 v25, v17, v114
	v_cvt_pk_bf16_f32 v98, v24, v25
	v_mul_f32_e32 v24, v16, v113
	v_mul_f32_e32 v25, v17, v115
	v_cvt_pk_bf16_f32 v106, v24, v25
	v_mul_f32_e32 v24, v18, v116
	v_mul_f32_e32 v25, v19, v118
	v_cvt_pk_bf16_f32 v99, v24, v25
	v_mul_f32_e32 v24, v18, v117
	v_mul_f32_e32 v25, v19, v119
	v_cvt_pk_bf16_f32 v107, v24, v25
.LBB0_783:
	ds_read2_b64 v[28:31], v51 offset0:1 offset1:161
	ds_read2_b64 v[24:27], v136 offset0:65 offset1:225
	ds_read_b64 v[114:115], v51 offset:5128
	v_lshlrev_b32_e32 v112, 16, v53
	v_and_b32_e32 v113, 0xffff0000, v53
	v_lshlrev_b32_e32 v126, 16, v57
	v_and_b32_e32 v127, 0xffff0000, v57
	s_waitcnt lgkmcnt(0)
	v_pk_fma_f32 v[112:113], v[28:29], v[112:113], v[114:115]
	v_lshlrev_b32_e32 v128, 16, v61
	v_and_b32_e32 v129, 0xffff0000, v61
	v_pk_fma_f32 v[112:113], v[30:31], v[126:127], v[112:113]
	v_lshlrev_b32_e32 v130, 16, v65
	v_and_b32_e32 v131, 0xffff0000, v65
	v_pk_fma_f32 v[112:113], v[24:25], v[128:129], v[112:113]
	v_pk_fma_f32 v[126:127], v[28:29], v[126:127], v[114:115]
	v_pk_fma_f32 v[112:113], v[26:27], v[130:131], v[112:113]
	v_pk_fma_f32 v[126:127], v[30:31], v[128:129], v[126:127]
	v_pk_mul_f32 v[140:141], v[112:113], s[78:79] op_sel_hi:[1,0]
	v_lshlrev_b32_e32 v132, 16, v69
	v_exp_f32_e32 v140, v140
	v_exp_f32_e32 v141, v141
	v_and_b32_e32 v133, 0xffff0000, v69
	v_pk_fma_f32 v[126:127], v[24:25], v[130:131], v[126:127]
	v_pk_fma_f32 v[128:129], v[28:29], v[128:129], v[114:115]
	v_pk_add_f32 v[140:141], v[140:141], 1.0 op_sel_hi:[1,0]
	v_pk_fma_f32 v[126:127], v[26:27], v[132:133], v[126:127]
	v_mul_f32_e32 v248, v140, v141
	v_rcp_f32_e32 v248, v248
	s_nop 0
	v_pk_mul_f32 v[140:141], v[140:141], v[248:249] op_sel:[1,0] op_sel_hi:[0,0]
	v_pk_fma_f32 v[128:129], v[30:31], v[130:131], v[128:129]
	v_lshlrev_b32_e32 v134, 16, v73
	v_and_b32_e32 v135, 0xffff0000, v73
	v_pk_mul_f32 v[112:113], v[112:113], v[140:141]
	v_pk_mul_f32 v[140:141], v[126:127], s[78:79] op_sel_hi:[1,0]
	v_pk_fma_f32 v[128:129], v[24:25], v[132:133], v[128:129]
	v_exp_f32_e32 v140, v140
	v_exp_f32_e32 v141, v141
	v_pk_fma_f32 v[128:129], v[26:27], v[134:135], v[128:129]
	v_pk_fma_f32 v[130:131], v[28:29], v[130:131], v[114:115]
	v_lshlrev_b32_e32 v124, 16, v77
	v_pk_add_f32 v[140:141], v[140:141], 1.0 op_sel_hi:[1,0]
	v_pk_fma_f32 v[130:131], v[30:31], v[132:133], v[130:131]
	v_mul_f32_e32 v250, v140, v141
	v_rcp_f32_e32 v250, v250
	s_nop 0
	v_pk_mul_f32 v[140:141], v[140:141], v[250:251] op_sel:[1,0] op_sel_hi:[0,0]
	v_and_b32_e32 v125, 0xffff0000, v77
	v_pk_fma_f32 v[130:131], v[24:25], v[134:135], v[130:131]
	v_pk_fma_f32 v[132:133], v[28:29], v[132:133], v[114:115]
	v_pk_mul_f32 v[126:127], v[126:127], v[140:141]
	v_pk_mul_f32 v[140:141], v[128:129], s[78:79] op_sel_hi:[1,0]
	v_pk_fma_f32 v[130:131], v[26:27], v[124:125], v[130:131]
	v_exp_f32_e32 v140, v140
	v_exp_f32_e32 v141, v141
	v_pk_fma_f32 v[132:133], v[30:31], v[134:135], v[132:133]
	v_lshlrev_b32_e32 v116, 16, v81
	v_and_b32_e32 v117, 0xffff0000, v81
	v_pk_add_f32 v[140:141], v[140:141], 1.0 op_sel_hi:[1,0]
	v_pk_fma_f32 v[132:133], v[24:25], v[124:125], v[132:133]
	v_mul_f32_e32 v242, v140, v141
	v_rcp_f32_e32 v242, v242
	s_nop 0
	v_pk_mul_f32 v[140:141], v[140:141], v[242:243] op_sel:[1,0] op_sel_hi:[0,0]
	v_pk_fma_f32 v[132:133], v[26:27], v[116:117], v[132:133]
	v_pk_fma_f32 v[134:135], v[28:29], v[134:135], v[114:115]
	v_lshlrev_b32_e32 v120, 16, v85
	v_pk_mul_f32 v[128:129], v[128:129], v[140:141]
	v_pk_mul_f32 v[140:141], v[130:131], s[78:79] op_sel_hi:[1,0]
	v_pk_fma_f32 v[134:135], v[30:31], v[124:125], v[134:135]
	v_exp_f32_e32 v140, v140
	v_exp_f32_e32 v141, v141
	v_and_b32_e32 v121, 0xffff0000, v85
	v_pk_fma_f32 v[134:135], v[24:25], v[116:117], v[134:135]
	v_pk_fma_f32 v[124:125], v[28:29], v[124:125], v[114:115]
	v_pk_add_f32 v[140:141], v[140:141], 1.0 op_sel_hi:[1,0]
	v_pk_fma_f32 v[134:135], v[26:27], v[120:121], v[134:135]
	v_mul_f32_e32 v244, v140, v141
	v_rcp_f32_e32 v244, v244
	s_nop 0
	v_pk_mul_f32 v[140:141], v[140:141], v[244:245] op_sel:[1,0] op_sel_hi:[0,0]
	v_pk_fma_f32 v[28:29], v[28:29], v[116:117], v[114:115]
	v_lshlrev_b32_e32 v122, 16, v89
	v_and_b32_e32 v123, 0xffff0000, v89
	v_pk_mul_f32 v[130:131], v[130:131], v[140:141]
	v_pk_mul_f32 v[140:141], v[132:133], s[78:79] op_sel_hi:[1,0]
	v_pk_fma_f32 v[124:125], v[30:31], v[116:117], v[124:125]
	v_exp_f32_e32 v140, v140
	v_exp_f32_e32 v141, v141
	v_pk_fma_f32 v[28:29], v[30:31], v[120:121], v[28:29]
	v_lshlrev_b32_e32 v118, 16, v93
	v_and_b32_e32 v119, 0xffff0000, v93
	v_pk_add_f32 v[140:141], v[140:141], 1.0 op_sel_hi:[1,0]
	v_pk_fma_f32 v[124:125], v[24:25], v[120:121], v[124:125]
	v_mul_f32_e32 v246, v140, v141
	v_rcp_f32_e32 v246, v246
	s_nop 0
	v_pk_mul_f32 v[140:141], v[140:141], v[246:247] op_sel:[1,0] op_sel_hi:[0,0]
	v_pk_fma_f32 v[24:25], v[24:25], v[122:123], v[28:29]
	v_pk_fma_f32 v[124:125], v[26:27], v[122:123], v[124:125]
	v_pk_fma_f32 v[24:25], v[26:27], v[118:119], v[24:25]
	v_pk_mul_f32 v[132:133], v[132:133], v[140:141]
	v_pk_mul_f32 v[140:141], v[134:135], s[78:79] op_sel_hi:[1,0]
	v_pk_mul_f32 v[26:27], v[24:25], s[78:79] op_sel_hi:[1,0]
	v_exp_f32_e32 v140, v140
	v_exp_f32_e32 v141, v141
	v_exp_f32_e32 v26, v26
	v_exp_f32_e32 v27, v27
	s_and_b64 vcc, exec, s[0:1]
	v_pk_add_f32 v[140:141], v[140:141], 1.0 op_sel_hi:[1,0]
	v_cvt_pk_bf16_f32 v33, v112, v113
	v_pk_add_f32 v[26:27], v[26:27], 1.0 op_sel_hi:[1,0]
	v_mul_f32_e32 v248, v140, v141
	v_rcp_f32_e32 v248, v248
	s_nop 0
	v_pk_mul_f32 v[140:141], v[140:141], v[248:249] op_sel:[1,0] op_sel_hi:[0,0]
	v_mul_f32_e32 v250, v26, v27
	v_rcp_f32_e32 v250, v250
	s_nop 0
	v_pk_mul_f32 v[26:27], v[26:27], v[250:251] op_sel:[1,0] op_sel_hi:[0,0]
	v_cvt_pk_bf16_f32 v35, v126, v127
	v_pk_mul_f32 v[134:135], v[134:135], v[140:141]
	v_pk_mul_f32 v[140:141], v[124:125], s[78:79] op_sel_hi:[1,0]
	v_pk_mul_f32 v[24:25], v[24:25], v[26:27]
	v_exp_f32_e32 v140, v140
	v_exp_f32_e32 v141, v141
	v_cvt_pk_bf16_f32 v37, v128, v129
	v_cvt_pk_bf16_f32 v39, v130, v131
	v_cvt_pk_bf16_f32 v41, v132, v133
	v_cvt_pk_bf16_f32 v43, v134, v135
	v_cvt_pk_bf16_f32 v47, v24, v25
	s_nop 0
	v_pk_add_f32 v[140:141], v[140:141], 1.0 op_sel_hi:[1,0]
	s_nop 0
	v_mul_f32_e32 v242, v140, v141
	v_rcp_f32_e32 v242, v242
	s_nop 0
	v_pk_mul_f32 v[140:141], v[140:141], v[242:243] op_sel:[1,0] op_sel_hi:[0,0]
	s_nop 0
	v_pk_mul_f32 v[124:125], v[124:125], v[140:141]
	s_nop 0
	v_cvt_pk_bf16_f32 v45, v124, v125
	s_cbranch_vccnz .LBB0_785
	v_mul_f32_e32 v26, v20, v112
	v_mul_f32_e32 v27, v21, v126
	v_cvt_pk_bf16_f32 v100, v26, v27
	v_mul_f32_e32 v26, v20, v113
	v_mul_f32_e32 v27, v21, v127
	v_cvt_pk_bf16_f32 v108, v26, v27
	v_mul_f32_e32 v26, v22, v128
	v_mul_f32_e32 v27, v23, v130
	v_cvt_pk_bf16_f32 v101, v26, v27
	v_mul_f32_e32 v26, v22, v129
	v_mul_f32_e32 v27, v23, v131
	v_cvt_pk_bf16_f32 v109, v26, v27
	v_mul_f32_e32 v26, v16, v132
	v_mul_f32_e32 v27, v17, v134
	v_cvt_pk_bf16_f32 v102, v26, v27
	v_mul_f32_e32 v26, v16, v133
	v_mul_f32_e32 v24, v19, v24
	v_mul_f32_e32 v27, v17, v135
	v_cvt_pk_bf16_f32 v110, v26, v27
	v_mul_f32_e32 v26, v18, v124
	v_cvt_pk_bf16_f32 v103, v26, v24
	v_mul_f32_e32 v24, v18, v125
	v_mul_f32_e32 v25, v19, v25
	v_cvt_pk_bf16_f32 v111, v24, v25

.LBB0_787:
	ds_read2_b64 v[42:45], v51 offset0:2 offset1:162
	ds_read2_b64 v[116:119], v136 offset0:66 offset1:226
	ds_read_b64 v[46:47], v51 offset:5136
	v_lshlrev_b32_e32 v24, 16, v54
	v_and_b32_e32 v25, 0xffff0000, v54
	v_lshlrev_b32_e32 v26, 16, v58
	v_and_b32_e32 v27, 0xffff0000, v58
	s_waitcnt lgkmcnt(0)
	v_pk_fma_f32 v[24:25], v[42:43], v[24:25], v[46:47]
	v_lshlrev_b32_e32 v28, 16, v62
	v_and_b32_e32 v29, 0xffff0000, v62
	v_pk_fma_f32 v[24:25], v[44:45], v[26:27], v[24:25]
	v_pk_fma_f32 v[26:27], v[42:43], v[26:27], v[46:47]
	v_lshlrev_b32_e32 v30, 16, v66
	v_and_b32_e32 v31, 0xffff0000, v66
	v_pk_fma_f32 v[26:27], v[44:45], v[28:29], v[26:27]
	v_lshlrev_b32_e32 v38, 16, v70
	v_and_b32_e32 v39, 0xffff0000, v70
	v_pk_fma_f32 v[26:27], v[116:117], v[30:31], v[26:27]
	v_pk_fma_f32 v[24:25], v[116:117], v[28:29], v[24:25]
	v_pk_fma_f32 v[26:27], v[118:119], v[38:39], v[26:27]
	v_pk_fma_f32 v[28:29], v[42:43], v[28:29], v[46:47]
	v_pk_mul_f32 v[34:35], v[26:27], s[78:79] op_sel_hi:[1,0]
	v_pk_fma_f32 v[28:29], v[44:45], v[30:31], v[28:29]
	v_exp_f32_e32 v34, v34
	v_exp_f32_e32 v35, v35
	v_lshlrev_b32_e32 v40, 16, v74
	v_and_b32_e32 v41, 0xffff0000, v74
	v_pk_fma_f32 v[28:29], v[116:117], v[38:39], v[28:29]
	v_pk_add_f32 v[34:35], v[34:35], 1.0 op_sel_hi:[1,0]
	v_pk_fma_f32 v[28:29], v[118:119], v[40:41], v[28:29]
	v_mul_f32_e32 v244, v34, v35
	v_rcp_f32_e32 v244, v244
	s_nop 0
	v_pk_mul_f32 v[34:35], v[34:35], v[244:245] op_sel:[1,0] op_sel_hi:[0,0]
	v_pk_fma_f32 v[24:25], v[118:119], v[30:31], v[24:25]
	v_pk_fma_f32 v[30:31], v[42:43], v[30:31], v[46:47]
	v_lshlrev_b32_e32 v120, 16, v78
	v_pk_mul_f32 v[26:27], v[26:27], v[34:35]
	v_pk_mul_f32 v[34:35], v[28:29], s[78:79] op_sel_hi:[1,0]
	v_pk_fma_f32 v[30:31], v[44:45], v[38:39], v[30:31]
	v_exp_f32_e32 v34, v34
	v_exp_f32_e32 v35, v35
	v_pk_fma_f32 v[38:39], v[42:43], v[38:39], v[46:47]
	v_and_b32_e32 v121, 0xffff0000, v78
	v_pk_fma_f32 v[30:31], v[116:117], v[40:41], v[30:31]
	v_pk_add_f32 v[34:35], v[34:35], 1.0 op_sel_hi:[1,0]
	v_pk_fma_f32 v[38:39], v[44:45], v[40:41], v[38:39]
	v_rcp_f32_e32 v112, v34
	v_rcp_f32_e32 v113, v35
	v_lshlrev_b32_e32 v122, 16, v82
	v_and_b32_e32 v123, 0xffff0000, v82
	v_pk_fma_f32 v[30:31], v[118:119], v[120:121], v[30:31]
	v_pk_fma_f32 v[38:39], v[116:117], v[120:121], v[38:39]
	v_pk_mul_f32 v[36:37], v[30:31], s[78:79] op_sel_hi:[1,0]
	v_pk_mul_f32 v[28:29], v[28:29], v[112:113]
	v_pk_fma_f32 v[112:113], v[118:119], v[122:123], v[38:39]
	v_exp_f32_e32 v36, v36
	v_exp_f32_e32 v37, v37
	v_pk_mul_f32 v[38:39], v[112:113], s[78:79] op_sel_hi:[1,0]
	v_pk_fma_f32 v[40:41], v[42:43], v[40:41], v[46:47]
	v_exp_f32_e32 v38, v38
	v_exp_f32_e32 v39, v39
	v_pk_add_f32 v[34:35], v[36:37], 1.0 op_sel_hi:[1,0]
	v_lshlrev_b32_e32 v124, 16, v86
	v_rcp_f32_e32 v114, v34
	v_rcp_f32_e32 v115, v35
	v_pk_add_f32 v[38:39], v[38:39], 1.0 op_sel_hi:[1,0]
	v_and_b32_e32 v125, 0xffff0000, v86
	v_pk_fma_f32 v[40:41], v[44:45], v[120:121], v[40:41]
	v_rcp_f32_e32 v130, v38
	v_rcp_f32_e32 v131, v39
	v_pk_fma_f32 v[120:121], v[42:43], v[120:121], v[46:47]
	v_pk_fma_f32 v[42:43], v[42:43], v[122:123], v[46:47]
	v_lshlrev_b32_e32 v126, 16, v90
	v_and_b32_e32 v127, 0xffff0000, v90
	v_pk_fma_f32 v[120:121], v[44:45], v[122:123], v[120:121]
	v_pk_fma_f32 v[42:43], v[44:45], v[124:125], v[42:43]
	v_lshlrev_b32_e32 v128, 16, v94
	v_and_b32_e32 v129, 0xffff0000, v94
	v_pk_fma_f32 v[40:41], v[116:117], v[122:123], v[40:41]
	v_pk_fma_f32 v[120:121], v[116:117], v[124:125], v[120:121]
	v_pk_fma_f32 v[42:43], v[116:117], v[126:127], v[42:43]
	v_pk_mul_f32 v[30:31], v[30:31], v[114:115]
	v_pk_fma_f32 v[114:115], v[118:119], v[124:125], v[40:41]
	v_pk_fma_f32 v[120:121], v[118:119], v[126:127], v[120:121]
	v_pk_fma_f32 v[46:47], v[118:119], v[128:129], v[42:43]
	v_pk_mul_f32 v[32:33], v[24:25], s[78:79] op_sel_hi:[1,0]
	v_pk_mul_f32 v[40:41], v[114:115], s[78:79] op_sel_hi:[1,0]
	v_pk_mul_f32 v[112:113], v[112:113], v[130:131]
	v_pk_mul_f32 v[130:131], v[120:121], s[78:79] op_sel_hi:[1,0]
	v_pk_mul_f32 v[42:43], v[46:47], s[78:79] op_sel_hi:[1,0]
	v_exp_f32_e32 v32, v32
	v_exp_f32_e32 v33, v33
	v_exp_f32_e32 v40, v40
	v_exp_f32_e32 v41, v41
	v_exp_f32_e32 v130, v130
	v_exp_f32_e32 v131, v131
	v_exp_f32_e32 v42, v42
	v_exp_f32_e32 v43, v43
	v_pk_add_f32 v[32:33], v[32:33], 1.0 op_sel_hi:[1,0]
	v_pk_add_f32 v[38:39], v[40:41], 1.0 op_sel_hi:[1,0]
	v_pk_add_f32 v[44:45], v[130:131], 1.0 op_sel_hi:[1,0]
	v_pk_add_f32 v[42:43], v[42:43], 1.0 op_sel_hi:[1,0]
	v_mul_f32_e32 v246, v32, v33
	v_rcp_f32_e32 v246, v246
	s_nop 0
	v_pk_mul_f32 v[32:33], v[32:33], v[246:247] op_sel:[1,0] op_sel_hi:[0,0]
	v_rcp_f32_e32 v132, v38
	v_rcp_f32_e32 v133, v39
	v_rcp_f32_e32 v116, v44
	v_rcp_f32_e32 v117, v45
	v_rcp_f32_e32 v118, v42
	v_rcp_f32_e32 v119, v43
	v_pk_mul_f32 v[24:25], v[24:25], v[32:33]
	v_pk_mul_f32 v[114:115], v[114:115], v[132:133]
	v_pk_mul_f32 v[116:117], v[120:121], v[116:117]
	v_pk_mul_f32 v[118:119], v[46:47], v[118:119]
	s_and_b64 vcc, exec, s[0:1]
	v_cvt_pk_bf16_f32 v32, v24, v25
	v_cvt_pk_bf16_f32 v34, v26, v27
	v_cvt_pk_bf16_f32 v36, v28, v29
	v_cvt_pk_bf16_f32 v38, v30, v31
	v_cvt_pk_bf16_f32 v40, v112, v113
	v_cvt_pk_bf16_f32 v44, v114, v115
	v_cvt_pk_bf16_f32 v42, v116, v117
	v_cvt_pk_bf16_f32 v46, v118, v119
	s_cbranch_vccnz .LBB0_789
	v_mul_f32_e32 v24, v20, v24
	v_mul_f32_e32 v26, v21, v26
	v_cvt_pk_bf16_f32 v96, v24, v26
	v_mul_f32_e32 v24, v20, v25
	v_mul_f32_e32 v25, v21, v27
	v_cvt_pk_bf16_f32 v104, v24, v25
	v_mul_f32_e32 v24, v22, v28
	v_mul_f32_e32 v25, v23, v30
	v_cvt_pk_bf16_f32 v97, v24, v25
	v_mul_f32_e32 v24, v22, v29
	v_mul_f32_e32 v25, v23, v31
	v_cvt_pk_bf16_f32 v105, v24, v25
	v_mul_f32_e32 v24, v16, v112
	v_mul_f32_e32 v25, v17, v114
	v_cvt_pk_bf16_f32 v98, v24, v25
	v_mul_f32_e32 v24, v16, v113
	v_mul_f32_e32 v25, v17, v115
	v_cvt_pk_bf16_f32 v106, v24, v25
	v_mul_f32_e32 v24, v18, v116
	v_mul_f32_e32 v25, v19, v118
	v_cvt_pk_bf16_f32 v99, v24, v25
	v_mul_f32_e32 v24, v18, v117
	v_mul_f32_e32 v25, v19, v119
	v_cvt_pk_bf16_f32 v107, v24, v25
.LBB0_789:
	ds_read2_b64 v[28:31], v51 offset0:3 offset1:163
	ds_read2_b64 v[24:27], v136 offset0:67 offset1:227
	ds_read_b64 v[114:115], v51 offset:5144
	v_lshlrev_b32_e32 v112, 16, v55
	v_and_b32_e32 v113, 0xffff0000, v55
	v_lshlrev_b32_e32 v124, 16, v59
	v_and_b32_e32 v125, 0xffff0000, v59
	s_waitcnt lgkmcnt(0)
	v_pk_fma_f32 v[112:113], v[28:29], v[112:113], v[114:115]
	v_lshlrev_b32_e32 v128, 16, v63
	v_and_b32_e32 v129, 0xffff0000, v63
	v_pk_fma_f32 v[112:113], v[30:31], v[124:125], v[112:113]
	v_lshlrev_b32_e32 v130, 16, v67
	v_and_b32_e32 v131, 0xffff0000, v67
	v_pk_fma_f32 v[112:113], v[24:25], v[128:129], v[112:113]
	v_pk_fma_f32 v[124:125], v[28:29], v[124:125], v[114:115]
	v_pk_fma_f32 v[112:113], v[26:27], v[130:131], v[112:113]
	v_pk_fma_f32 v[124:125], v[30:31], v[128:129], v[124:125]
	v_pk_mul_f32 v[140:141], v[112:113], s[78:79] op_sel_hi:[1,0]
	v_lshlrev_b32_e32 v132, 16, v71
	v_exp_f32_e32 v140, v140
	v_exp_f32_e32 v141, v141
	v_and_b32_e32 v133, 0xffff0000, v71
	v_pk_fma_f32 v[124:125], v[24:25], v[130:131], v[124:125]
	v_pk_fma_f32 v[128:129], v[28:29], v[128:129], v[114:115]
	v_pk_add_f32 v[140:141], v[140:141], 1.0 op_sel_hi:[1,0]
	v_pk_fma_f32 v[124:125], v[26:27], v[132:133], v[124:125]
	v_mul_f32_e32 v248, v140, v141
	v_rcp_f32_e32 v248, v248
	s_nop 0
	v_pk_mul_f32 v[140:141], v[140:141], v[248:249] op_sel:[1,0] op_sel_hi:[0,0]
	v_pk_fma_f32 v[128:129], v[30:31], v[130:131], v[128:129]
	v_lshlrev_b32_e32 v134, 16, v75
	v_and_b32_e32 v135, 0xffff0000, v75
	v_pk_mul_f32 v[112:113], v[112:113], v[140:141]
	v_pk_mul_f32 v[140:141], v[124:125], s[78:79] op_sel_hi:[1,0]
	v_pk_fma_f32 v[128:129], v[24:25], v[132:133], v[128:129]
	v_exp_f32_e32 v140, v140
	v_exp_f32_e32 v141, v141
	v_pk_fma_f32 v[128:129], v[26:27], v[134:135], v[128:129]
	v_pk_fma_f32 v[130:131], v[28:29], v[130:131], v[114:115]
	v_lshlrev_b32_e32 v126, 16, v79
	v_pk_add_f32 v[140:141], v[140:141], 1.0 op_sel_hi:[1,0]
	v_pk_fma_f32 v[130:131], v[30:31], v[132:133], v[130:131]
	v_mul_f32_e32 v250, v140, v141
	v_rcp_f32_e32 v250, v250
	s_nop 0
	v_pk_mul_f32 v[140:141], v[140:141], v[250:251] op_sel:[1,0] op_sel_hi:[0,0]
	v_and_b32_e32 v127, 0xffff0000, v79
	v_pk_fma_f32 v[130:131], v[24:25], v[134:135], v[130:131]
	v_pk_fma_f32 v[132:133], v[28:29], v[132:133], v[114:115]
	v_pk_mul_f32 v[124:125], v[124:125], v[140:141]
	v_pk_mul_f32 v[140:141], v[128:129], s[78:79] op_sel_hi:[1,0]
	v_pk_fma_f32 v[130:131], v[26:27], v[126:127], v[130:131]
	v_exp_f32_e32 v140, v140
	v_exp_f32_e32 v141, v141
	v_pk_fma_f32 v[132:133], v[30:31], v[134:135], v[132:133]
	v_lshlrev_b32_e32 v116, 16, v83
	v_and_b32_e32 v117, 0xffff0000, v83
	v_pk_add_f32 v[140:141], v[140:141], 1.0 op_sel_hi:[1,0]
	v_pk_fma_f32 v[132:133], v[24:25], v[126:127], v[132:133]
	v_mul_f32_e32 v242, v140, v141
	v_rcp_f32_e32 v242, v242
	s_nop 0
	v_pk_mul_f32 v[140:141], v[140:141], v[242:243] op_sel:[1,0] op_sel_hi:[0,0]
	v_pk_fma_f32 v[132:133], v[26:27], v[116:117], v[132:133]
	v_pk_fma_f32 v[134:135], v[28:29], v[134:135], v[114:115]
	v_lshlrev_b32_e32 v120, 16, v87
	v_pk_mul_f32 v[128:129], v[128:129], v[140:141]
	v_pk_mul_f32 v[140:141], v[130:131], s[78:79] op_sel_hi:[1,0]
	v_pk_fma_f32 v[134:135], v[30:31], v[126:127], v[134:135]
	v_exp_f32_e32 v140, v140
	v_exp_f32_e32 v141, v141
	v_and_b32_e32 v121, 0xffff0000, v87
	v_pk_fma_f32 v[134:135], v[24:25], v[116:117], v[134:135]
	v_pk_fma_f32 v[126:127], v[28:29], v[126:127], v[114:115]
	v_pk_add_f32 v[140:141], v[140:141], 1.0 op_sel_hi:[1,0]
	v_pk_fma_f32 v[134:135], v[26:27], v[120:121], v[134:135]
	v_mul_f32_e32 v244, v140, v141
	v_rcp_f32_e32 v244, v244
	s_nop 0
	v_pk_mul_f32 v[140:141], v[140:141], v[244:245] op_sel:[1,0] op_sel_hi:[0,0]
	v_pk_fma_f32 v[28:29], v[28:29], v[116:117], v[114:115]
	v_lshlrev_b32_e32 v122, 16, v91
	v_and_b32_e32 v123, 0xffff0000, v91
	v_pk_mul_f32 v[130:131], v[130:131], v[140:141]
	v_pk_mul_f32 v[140:141], v[132:133], s[78:79] op_sel_hi:[1,0]
	v_pk_fma_f32 v[126:127], v[30:31], v[116:117], v[126:127]
	v_exp_f32_e32 v140, v140
	v_exp_f32_e32 v141, v141
	v_pk_fma_f32 v[28:29], v[30:31], v[120:121], v[28:29]
	v_lshlrev_b32_e32 v118, 16, v95
	v_and_b32_e32 v119, 0xffff0000, v95
	v_pk_add_f32 v[140:141], v[140:141], 1.0 op_sel_hi:[1,0]
	v_pk_fma_f32 v[126:127], v[24:25], v[120:121], v[126:127]
	v_mul_f32_e32 v246, v140, v141
	v_rcp_f32_e32 v246, v246
	s_nop 0
	v_pk_mul_f32 v[140:141], v[140:141], v[246:247] op_sel:[1,0] op_sel_hi:[0,0]
	v_pk_fma_f32 v[24:25], v[24:25], v[122:123], v[28:29]
	v_pk_fma_f32 v[126:127], v[26:27], v[122:123], v[126:127]
	v_pk_fma_f32 v[24:25], v[26:27], v[118:119], v[24:25]
	v_pk_mul_f32 v[132:133], v[132:133], v[140:141]
	v_pk_mul_f32 v[140:141], v[134:135], s[78:79] op_sel_hi:[1,0]
	v_pk_mul_f32 v[26:27], v[24:25], s[78:79] op_sel_hi:[1,0]
	v_exp_f32_e32 v140, v140
	v_exp_f32_e32 v141, v141
	v_exp_f32_e32 v26, v26
	v_exp_f32_e32 v27, v27
	s_and_b64 vcc, exec, s[0:1]
	v_pk_add_f32 v[140:141], v[140:141], 1.0 op_sel_hi:[1,0]
	v_cvt_pk_bf16_f32 v33, v112, v113
	v_pk_add_f32 v[26:27], v[26:27], 1.0 op_sel_hi:[1,0]
	v_mul_f32_e32 v248, v140, v141
	v_rcp_f32_e32 v248, v248
	s_nop 0
	v_pk_mul_f32 v[140:141], v[140:141], v[248:249] op_sel:[1,0] op_sel_hi:[0,0]
	v_mul_f32_e32 v250, v26, v27
	v_rcp_f32_e32 v250, v250
	s_nop 0
	v_pk_mul_f32 v[26:27], v[26:27], v[250:251] op_sel:[1,0] op_sel_hi:[0,0]
	v_cvt_pk_bf16_f32 v35, v124, v125
	v_pk_mul_f32 v[134:135], v[134:135], v[140:141]
	v_pk_mul_f32 v[140:141], v[126:127], s[78:79] op_sel_hi:[1,0]
	v_pk_mul_f32 v[24:25], v[24:25], v[26:27]
	v_exp_f32_e32 v140, v140
	v_exp_f32_e32 v141, v141
	v_cvt_pk_bf16_f32 v37, v128, v129
	v_cvt_pk_bf16_f32 v39, v130, v131
	v_cvt_pk_bf16_f32 v41, v132, v133
	v_cvt_pk_bf16_f32 v45, v134, v135
	v_cvt_pk_bf16_f32 v47, v24, v25
	s_nop 0
	v_pk_add_f32 v[140:141], v[140:141], 1.0 op_sel_hi:[1,0]
	s_nop 0
	v_mul_f32_e32 v242, v140, v141
	v_rcp_f32_e32 v242, v242
	s_nop 0
	v_pk_mul_f32 v[140:141], v[140:141], v[242:243] op_sel:[1,0] op_sel_hi:[0,0]
	s_nop 0
	v_pk_mul_f32 v[126:127], v[126:127], v[140:141]
	s_nop 0
	v_cvt_pk_bf16_f32 v43, v126, v127
	s_cbranch_vccnz .LBB0_791
	v_mul_f32_e32 v26, v20, v112
	v_mul_f32_e32 v27, v21, v124
	v_mul_f32_e32 v20, v20, v113
	v_mul_f32_e32 v21, v21, v125
	v_cvt_pk_bf16_f32 v108, v20, v21
	v_mul_f32_e32 v20, v22, v128
	v_mul_f32_e32 v21, v23, v130
	v_cvt_pk_bf16_f32 v101, v20, v21
	v_mul_f32_e32 v20, v22, v129
	v_mul_f32_e32 v21, v23, v131
	v_cvt_pk_bf16_f32 v109, v20, v21
	v_mul_f32_e32 v20, v16, v132
	v_mul_f32_e32 v21, v17, v134
	v_mul_f32_e32 v16, v16, v133
	v_mul_f32_e32 v17, v17, v135
	v_cvt_pk_bf16_f32 v110, v16, v17
	v_mul_f32_e32 v16, v18, v126
	v_mul_f32_e32 v17, v19, v24
	v_cvt_pk_bf16_f32 v100, v26, v27
	v_cvt_pk_bf16_f32 v102, v20, v21
	v_cvt_pk_bf16_f32 v103, v16, v17
	v_mul_f32_e32 v16, v18, v127
	v_mul_f32_e32 v17, v19, v25
	v_cvt_pk_bf16_f32 v111, v16, v17

.LBB0_793:
	v_mov_b32_e32 v51, v144
	v_and_b32_e32 v25, 0xffff0000, v145
	v_lshlrev_b32_e32 v16, 1, v51
	v_and_b32_e32 v114, 62, v16
	v_lshl_add_u32 v16, v114, 2, 0
	v_add_u32_e32 v24, 0x23000, v16
	v_add_u32_e32 v16, 0x800, v24
	ds_read2_b64 v[20:23], v24 offset1:160
	ds_read2_b64 v[16:19], v16 offset0:64 offset1:224
	ds_read_b64 v[26:27], v24 offset:5120
	v_lshlrev_b32_e32 v24, 16, v145
	v_lshlrev_b32_e32 v36, 16, v150
	v_and_b32_e32 v37, 0xffff0000, v150
	v_lshlrev_b32_e32 v38, 16, v151
	s_waitcnt lgkmcnt(0)
	v_pk_fma_f32 v[24:25], v[20:21], v[24:25], v[26:27]
	v_and_b32_e32 v39, 0xffff0000, v151
	v_pk_fma_f32 v[24:25], v[22:23], v[36:37], v[24:25]
	v_lshlrev_b32_e32 v40, 16, v48
	v_and_b32_e32 v41, 0xffff0000, v48
	v_pk_fma_f32 v[24:25], v[16:17], v[38:39], v[24:25]
	v_pk_fma_f32 v[36:37], v[20:21], v[36:37], v[26:27]
	v_pk_fma_f32 v[24:25], v[18:19], v[40:41], v[24:25]
	v_pk_fma_f32 v[36:37], v[22:23], v[38:39], v[36:37]
	v_pk_mul_f32 v[112:113], v[24:25], s[78:79] op_sel_hi:[1,0]
	v_lshlrev_b32_e32 v42, 16, v153
	v_exp_f32_e32 v112, v112
	v_exp_f32_e32 v113, v113
	v_and_b32_e32 v43, 0xffff0000, v153
	v_pk_fma_f32 v[36:37], v[16:17], v[40:41], v[36:37]
	v_pk_fma_f32 v[38:39], v[20:21], v[38:39], v[26:27]
	v_pk_add_f32 v[112:113], v[112:113], 1.0 op_sel_hi:[1,0]
	v_pk_fma_f32 v[36:37], v[18:19], v[42:43], v[36:37]
	v_mul_f32_e32 v244, v112, v113
	v_rcp_f32_e32 v244, v244
	s_nop 0
	v_pk_mul_f32 v[112:113], v[112:113], v[244:245] op_sel:[1,0] op_sel_hi:[0,0]
	v_pk_fma_f32 v[38:39], v[22:23], v[40:41], v[38:39]
	v_lshlrev_b32_e32 v44, 16, v152
	v_and_b32_e32 v45, 0xffff0000, v152
	v_pk_mul_f32 v[24:25], v[24:25], v[112:113]
	v_pk_mul_f32 v[112:113], v[36:37], s[78:79] op_sel_hi:[1,0]
	v_pk_fma_f32 v[38:39], v[16:17], v[42:43], v[38:39]
	v_exp_f32_e32 v112, v112
	v_exp_f32_e32 v113, v113
	v_pk_fma_f32 v[38:39], v[18:19], v[44:45], v[38:39]
	v_pk_fma_f32 v[40:41], v[20:21], v[40:41], v[26:27]
	v_lshlrev_b32_e32 v46, 16, v158
	v_pk_add_f32 v[112:113], v[112:113], 1.0 op_sel_hi:[1,0]
	v_pk_fma_f32 v[40:41], v[22:23], v[42:43], v[40:41]
	v_mul_f32_e32 v246, v112, v113
	v_rcp_f32_e32 v246, v246
	s_nop 0
	v_pk_mul_f32 v[112:113], v[112:113], v[246:247] op_sel:[1,0] op_sel_hi:[0,0]
	v_and_b32_e32 v47, 0xffff0000, v158
	v_pk_fma_f32 v[40:41], v[16:17], v[44:45], v[40:41]
	v_pk_fma_f32 v[42:43], v[20:21], v[42:43], v[26:27]
	v_pk_mul_f32 v[36:37], v[36:37], v[112:113]
	v_pk_mul_f32 v[112:113], v[38:39], s[78:79] op_sel_hi:[1,0]
	v_pk_fma_f32 v[40:41], v[18:19], v[46:47], v[40:41]
	v_exp_f32_e32 v112, v112
	v_exp_f32_e32 v113, v113
	v_pk_fma_f32 v[42:43], v[22:23], v[44:45], v[42:43]
	v_lshlrev_b32_e32 v28, 16, v157
	v_and_b32_e32 v29, 0xffff0000, v157
	v_pk_add_f32 v[112:113], v[112:113], 1.0 op_sel_hi:[1,0]
	v_pk_fma_f32 v[42:43], v[16:17], v[46:47], v[42:43]
	v_mul_f32_e32 v248, v112, v113
	v_rcp_f32_e32 v248, v248
	s_nop 0
	v_pk_mul_f32 v[112:113], v[112:113], v[248:249] op_sel:[1,0] op_sel_hi:[0,0]
	v_pk_fma_f32 v[42:43], v[18:19], v[28:29], v[42:43]
	v_pk_fma_f32 v[44:45], v[20:21], v[44:45], v[26:27]
	v_lshlrev_b32_e32 v32, 16, v160
	v_pk_mul_f32 v[38:39], v[38:39], v[112:113]
	v_pk_mul_f32 v[112:113], v[40:41], s[78:79] op_sel_hi:[1,0]
	v_pk_fma_f32 v[44:45], v[22:23], v[46:47], v[44:45]
	v_exp_f32_e32 v112, v112
	v_exp_f32_e32 v113, v113
	v_and_b32_e32 v33, 0xffff0000, v160
	v_pk_fma_f32 v[44:45], v[16:17], v[28:29], v[44:45]
	v_pk_fma_f32 v[46:47], v[20:21], v[46:47], v[26:27]
	v_pk_add_f32 v[112:113], v[112:113], 1.0 op_sel_hi:[1,0]
	v_pk_fma_f32 v[44:45], v[18:19], v[32:33], v[44:45]
	v_mul_f32_e32 v250, v112, v113
	v_rcp_f32_e32 v250, v250
	s_nop 0
	v_pk_mul_f32 v[112:113], v[112:113], v[250:251] op_sel:[1,0] op_sel_hi:[0,0]
	v_pk_fma_f32 v[20:21], v[20:21], v[28:29], v[26:27]
	v_lshlrev_b32_e32 v34, 16, v159
	v_and_b32_e32 v35, 0xffff0000, v159
	v_pk_mul_f32 v[40:41], v[40:41], v[112:113]
	v_pk_mul_f32 v[112:113], v[42:43], s[78:79] op_sel_hi:[1,0]
	v_pk_fma_f32 v[46:47], v[22:23], v[28:29], v[46:47]
	v_exp_f32_e32 v112, v112
	v_exp_f32_e32 v113, v113
	v_pk_fma_f32 v[20:21], v[22:23], v[32:33], v[20:21]
	v_lshlrev_b32_e32 v30, 16, v161
	v_and_b32_e32 v31, 0xffff0000, v161
	v_pk_add_f32 v[112:113], v[112:113], 1.0 op_sel_hi:[1,0]
	v_pk_fma_f32 v[46:47], v[16:17], v[32:33], v[46:47]
	v_mul_f32_e32 v242, v112, v113
	v_rcp_f32_e32 v242, v242
	s_nop 0
	v_pk_mul_f32 v[112:113], v[112:113], v[242:243] op_sel:[1,0] op_sel_hi:[0,0]
	v_pk_fma_f32 v[16:17], v[16:17], v[34:35], v[20:21]
	v_pk_fma_f32 v[46:47], v[18:19], v[34:35], v[46:47]
	v_pk_fma_f32 v[16:17], v[18:19], v[30:31], v[16:17]
	v_pk_mul_f32 v[42:43], v[42:43], v[112:113]
	v_pk_mul_f32 v[112:113], v[44:45], s[78:79] op_sel_hi:[1,0]
	v_pk_mul_f32 v[18:19], v[16:17], s[78:79] op_sel_hi:[1,0]
	v_exp_f32_e32 v112, v112
	v_exp_f32_e32 v113, v113
	v_exp_f32_e32 v18, v18
	v_exp_f32_e32 v19, v19
	s_lshl_b32 s37, s35, 7
	v_pk_add_f32 v[112:113], v[112:113], 1.0 op_sel_hi:[1,0]
	s_cmp_eq_u32 s35, 15
	v_mul_f32_e32 v244, v112, v113
	v_rcp_f32_e32 v244, v244
	s_nop 0
	v_pk_mul_f32 v[112:113], v[112:113], v[244:245] op_sel:[1,0] op_sel_hi:[0,0]
	v_pk_add_f32 v[18:19], v[18:19], 1.0 op_sel_hi:[1,0]
	v_cvt_pk_bf16_f32 v20, v25, v37
	v_mul_u32_u24_e32 v25, 0x110, v114
	v_pk_mul_f32 v[44:45], v[44:45], v[112:113]
	v_pk_mul_f32 v[112:113], v[46:47], s[78:79] op_sel_hi:[1,0]
	v_rcp_f32_e32 v18, v18
	v_exp_f32_e32 v112, v112
	v_exp_f32_e32 v113, v113
	v_rcp_f32_e32 v19, v19
	s_cselect_b64 s[0:1], -1, 0
	s_and_b64 vcc, exec, s[0:1]
	v_pk_add_f32 v[112:113], v[112:113], 1.0 op_sel_hi:[1,0]
	v_pk_mul_f32 v[22:23], v[16:17], v[18:19]
	v_mul_f32_e32 v246, v112, v113
	v_rcp_f32_e32 v246, v246
	s_nop 0
	v_pk_mul_f32 v[112:113], v[112:113], v[246:247] op_sel:[1,0] op_sel_hi:[0,0]
	v_cvt_pk_bf16_f32 v16, v24, v36
	v_lshrrev_b32_e32 v24, 5, v51
	v_xor_b32_e32 v24, v24, v51
	v_lshlrev_b32_e32 v24, 4, v24
	v_and_b32_e32 v24, 0xf0, v24
	v_pk_mul_f32 v[46:47], v[46:47], v[112:113]
	v_cvt_pk_bf16_f32 v17, v38, v40
	v_cvt_pk_bf16_f32 v18, v42, v44
	v_add3_u32 v24, 0, v24, v25
	v_cvt_pk_bf16_f32 v19, v46, v22
	v_cvt_pk_bf16_f32 v21, v39, v41
	v_cvt_pk_bf16_f32 v22, v43, v45
	v_cvt_pk_bf16_f32 v23, v47, v23
	ds_write_b128 v24, v[16:19]
	ds_write_b128 v24, v[20:23] offset:272
	s_cbranch_vccnz .LBB0_818
	v_mov_b32_e32 v18, v144
	s_or_b32 s6, s37, 0x7d
	v_lshrrev_b32_e32 v17, 1, v18
	v_lshlrev_b32_e32 v16, 3, v18
	v_and_b32_e32 v17, 0x78, v17
	s_add_i32 s7, s6, s9
	v_and_b32_e32 v16, 0x78, v16
	v_add_u32_e32 v17, s7, v17
	v_mul_lo_u32 v17, v17, s18
	v_or_b32_e32 v16, s31, v16
	v_add_lshl_u32 v17, v16, v17, 1
	global_load_dwordx4 v[52:55], v17, s[4:5]
	v_lshlrev_b32_e32 v16, 1, v18
	v_ashrrev_i32_e32 v18, 2, v18
	v_and_b32_e32 v18, -8, v18
	v_add_u32_e32 v19, s6, v18
	v_add_u32_e32 v18, s9, v19
	v_mul_lo_u32 v18, v18, s18
	v_and_or_b32 v20, v16, 62, s25
	v_add_lshl_u32 v18, v20, v18, 1
	v_cmp_lt_i32_e32 vcc, -1, v19
	v_mov_b32_e32 v150, 0
	v_mov_b32_e32 v145, 0
	s_and_saveexec_b64 s[6:7], vcc
	s_cbranch_execz .LBB0_796
	global_load_dword v145, v18, s[4:5]
